# nt cache hints plus panel barrier at stage3->out-proj, batched k-mean sums, DPP butterfly in memory attention
# speedup vs baseline: 1.1135x; 1.0041x over previous
; #define LAS __attribute__((address_space(3)))
;     __device__ __forceinline__ void operator()(const f32x4 (&acc)[2][2][4][2], const Unit& u, int wr, int wc, int fr, int fq, LAS unsigned char* lds) const {
;         const int row0 = u.pm * BM + wr * 64 + fr; const int col0 = u.pn * BM + wc * 32 + 8 * fq;
;         LAS float* part = (LAS float*)(lds + 131072);
;         f32x4 gg[2][2];
; #pragma unroll
;         for (int bj = 0; bj < 2; ++bj)
; #pragma unroll
;             for (int n = 0; n < 2; ++n) gg[bj][n] = *(const f32x4*)(g + col0 + bj * HALF + 4 * n);
; #pragma unroll
;         for (int ai = 0; ai < 2; ++ai)
; #pragma unroll
;             for (int m = 0; m < 4; ++m) { const size_t ro = (size_t)(row0 + ai * HALF + m * 16) * ldc + col0; float ssq = 0.f;
; #pragma unroll
;                 for (int bj = 0; bj < 2; ++bj) { const size_t o = ro + bj * HALF;
;                     const f32x4 r0 = *(const f32x4*)(res + o), r1 = *(const f32x4*)(res + o + 4);
.Lb3_join:
	s_or_b64 exec, exec, s[14:15]
	s_barrier
.Lb3_skip:
	s_lshl_b32 s46, s4, 8
	v_readlane_b32 s4, v244, 0
	v_readlane_b32 s5, v244, 1
	v_and_b32_e32 v25, 8, v172
	v_sub_u32_e32 v26, v172, v25
	v_add_u32_e32 v26, s46, v26
	v_lshl_or_b32 v27, s56, 8, v174
	v_lshrrev_b32_e32 v25, 1, v25
	v_add_u32_e32 v27, v27, v25
	v_lshl_add_u32 v28, v26, 10, v27
	v_lshlrev_b32_e32 v170, 2, v28
	v_lshlrev_b32_e32 v247, 1, v28
	v_lshlrev_b32_e32 v27, 2, v27
	v_add_u32_e32 v171, 0x8000, v170
	v_add_u32_e32 v24, 0x4000, v247
	v_mov_b32_e32 v177, v170
	v_mov_b32_e32 v195, v171
	v_lshlrev_b32_e32 v54, 2, v193
	v_lshlrev_b32_e32 v55, 2, v194
	global_load_dwordx4 v[180:183], v27, s[4:5]
	global_load_dwordx4 v[166:169], v27, s[4:5] offset:512
	global_load_dwordx4 v[196:199], v170, s[80:81] nt
	global_load_dwordx4 v[200:203], v170, s[80:81] offset:512 nt
	global_load_dwordx4 v[204:207], v171, s[80:81] nt
	global_load_dwordx4 v[208:211], v171, s[80:81] offset:512 nt
	v_add_u32_e32 v170, 0x10000, v170
	v_add_u32_e32 v171, 0x10000, v171
	global_load_dwordx4 v[212:215], v170, s[80:81] nt
	global_load_dwordx4 v[216:219], v170, s[80:81] offset:512 nt
	global_load_dwordx4 v[220:223], v171, s[80:81] nt
	global_load_dwordx4 v[224:227], v171, s[80:81] offset:512 nt
	v_add_u32_e32 v170, 0x10000, v170
	v_add_u32_e32 v171, 0x10000, v171
	global_load_dwordx4 v[228:231], v170, s[80:81] nt
	global_load_dwordx4 v[232:235], v170, s[80:81] offset:512 nt
	global_load_dwordx4 v[236:239], v171, s[80:81] nt
	global_load_dwordx4 v[240:243], v171, s[80:81] offset:512 nt
	v_add_u32_e32 v170, 0x10000, v170
	v_add_u32_e32 v171, 0x10000, v171
	v_mov_b32_dpp v25, v140 row_ror:8 row_mask:0xf bank_mask:0xf
	v_mov_b32_dpp v26, v141 row_ror:8 row_mask:0xf bank_mask:0xf
	v_mov_b32_dpp v140, v136 row_ror:8 row_mask:0xf bank_mask:0xc
	v_mov_b32_dpp v141, v137 row_ror:8 row_mask:0xf bank_mask:0xc
	v_mov_b32_dpp v136, v25 quad_perm:[0,1,2,3] row_mask:0xf bank_mask:0x3
	v_mov_b32_dpp v137, v26 quad_perm:[0,1,2,3] row_mask:0xf bank_mask:0x3
	v_mov_b32_dpp v25, v142 row_ror:8 row_mask:0xf bank_mask:0xf
	v_mov_b32_dpp v26, v143 row_ror:8 row_mask:0xf bank_mask:0xf
	v_mov_b32_dpp v142, v138 row_ror:8 row_mask:0xf bank_mask:0xc
	v_mov_b32_dpp v143, v139 row_ror:8 row_mask:0xf bank_mask:0xc
	v_mov_b32_dpp v138, v25 quad_perm:[0,1,2,3] row_mask:0xf bank_mask:0x3
	v_mov_b32_dpp v139, v26 quad_perm:[0,1,2,3] row_mask:0xf bank_mask:0x3
	v_mov_b32_dpp v25, v132 row_ror:8 row_mask:0xf bank_mask:0xf
	v_mov_b32_dpp v26, v133 row_ror:8 row_mask:0xf bank_mask:0xf
	v_mov_b32_dpp v132, v128 row_ror:8 row_mask:0xf bank_mask:0xc
	v_mov_b32_dpp v133, v129 row_ror:8 row_mask:0xf bank_mask:0xc
	v_mov_b32_dpp v128, v25 quad_perm:[0,1,2,3] row_mask:0xf bank_mask:0x3
	v_mov_b32_dpp v129, v26 quad_perm:[0,1,2,3] row_mask:0xf bank_mask:0x3
	v_mov_b32_dpp v25, v134 row_ror:8 row_mask:0xf bank_mask:0xf
	v_mov_b32_dpp v26, v135 row_ror:8 row_mask:0xf bank_mask:0xf
	v_mov_b32_dpp v134, v130 row_ror:8 row_mask:0xf bank_mask:0xc
	v_mov_b32_dpp v135, v131 row_ror:8 row_mask:0xf bank_mask:0xc
	v_mov_b32_dpp v130, v25 quad_perm:[0,1,2,3] row_mask:0xf bank_mask:0x3
	v_mov_b32_dpp v131, v26 quad_perm:[0,1,2,3] row_mask:0xf bank_mask:0x3
	v_mov_b32_dpp v25, v124 row_ror:8 row_mask:0xf bank_mask:0xf
	v_mov_b32_dpp v26, v125 row_ror:8 row_mask:0xf bank_mask:0xf
	v_mov_b32_dpp v124, v120 row_ror:8 row_mask:0xf bank_mask:0xc
	v_mov_b32_dpp v125, v121 row_ror:8 row_mask:0xf bank_mask:0xc
	v_mov_b32_dpp v120, v25 quad_perm:[0,1,2,3] row_mask:0xf bank_mask:0x3
	v_mov_b32_dpp v121, v26 quad_perm:[0,1,2,3] row_mask:0xf bank_mask:0x3
	v_mov_b32_dpp v25, v126 row_ror:8 row_mask:0xf bank_mask:0xf
	v_mov_b32_dpp v26, v127 row_ror:8 row_mask:0xf bank_mask:0xf
	v_mov_b32_dpp v126, v122 row_ror:8 row_mask:0xf bank_mask:0xc
	v_mov_b32_dpp v127, v123 row_ror:8 row_mask:0xf bank_mask:0xc
	v_mov_b32_dpp v122, v25 quad_perm:[0,1,2,3] row_mask:0xf bank_mask:0x3
	v_mov_b32_dpp v123, v26 quad_perm:[0,1,2,3] row_mask:0xf bank_mask:0x3
	v_mov_b32_dpp v25, v116 row_ror:8 row_mask:0xf bank_mask:0xf
	v_mov_b32_dpp v26, v117 row_ror:8 row_mask:0xf bank_mask:0xf
	v_mov_b32_dpp v116, v112 row_ror:8 row_mask:0xf bank_mask:0xc
	v_mov_b32_dpp v117, v113 row_ror:8 row_mask:0xf bank_mask:0xc
	v_mov_b32_dpp v112, v25 quad_perm:[0,1,2,3] row_mask:0xf bank_mask:0x3
	v_mov_b32_dpp v113, v26 quad_perm:[0,1,2,3] row_mask:0xf bank_mask:0x3
	v_mov_b32_dpp v25, v118 row_ror:8 row_mask:0xf bank_mask:0xf
	v_mov_b32_dpp v26, v119 row_ror:8 row_mask:0xf bank_mask:0xf
	v_mov_b32_dpp v118, v114 row_ror:8 row_mask:0xf bank_mask:0xc
	v_mov_b32_dpp v119, v115 row_ror:8 row_mask:0xf bank_mask:0xc
	v_mov_b32_dpp v114, v25 quad_perm:[0,1,2,3] row_mask:0xf bank_mask:0x3
	v_mov_b32_dpp v115, v26 quad_perm:[0,1,2,3] row_mask:0xf bank_mask:0x3
	v_mov_b32_dpp v25, v108 row_ror:8 row_mask:0xf bank_mask:0xf
	v_mov_b32_dpp v26, v109 row_ror:8 row_mask:0xf bank_mask:0xf
	v_mov_b32_dpp v108, v104 row_ror:8 row_mask:0xf bank_mask:0xc
	v_mov_b32_dpp v109, v105 row_ror:8 row_mask:0xf bank_mask:0xc
	v_mov_b32_dpp v104, v25 quad_perm:[0,1,2,3] row_mask:0xf bank_mask:0x3
	v_mov_b32_dpp v105, v26 quad_perm:[0,1,2,3] row_mask:0xf bank_mask:0x3
	v_mov_b32_dpp v25, v110 row_ror:8 row_mask:0xf bank_mask:0xf
	v_mov_b32_dpp v26, v111 row_ror:8 row_mask:0xf bank_mask:0xf
	v_mov_b32_dpp v110, v106 row_ror:8 row_mask:0xf bank_mask:0xc
	v_mov_b32_dpp v111, v107 row_ror:8 row_mask:0xf bank_mask:0xc
	v_mov_b32_dpp v106, v25 quad_perm:[0,1,2,3] row_mask:0xf bank_mask:0x3
	v_mov_b32_dpp v107, v26 quad_perm:[0,1,2,3] row_mask:0xf bank_mask:0x3
	v_mov_b32_dpp v25, v100 row_ror:8 row_mask:0xf bank_mask:0xf
;     __device__ __forceinline__ void operator()(const f32x4 (&acc)[2][2][4][2], const Unit& u, int wr, int wc, int fr, int fq, LAS unsigned char* lds) const {
;     ...
;                     const f32x4 r0 = *(const f32x4*)(res + o), r1 = *(const f32x4*)(res + o + 4);
;                     const f32x4 x0 = r0 + acc[ai][bj][m][0], x1 = r1 + acc[ai][bj][m][1];
;                     *(f32x4*)(O + o) = x0; *(f32x4*)(O + o + 4) = x1;
	v_mov_b32_dpp v26, v101 row_ror:8 row_mask:0xf bank_mask:0xf
	v_mov_b32_dpp v100, v96 row_ror:8 row_mask:0xf bank_mask:0xc
	v_mov_b32_dpp v101, v97 row_ror:8 row_mask:0xf bank_mask:0xc
	v_mov_b32_dpp v96, v25 quad_perm:[0,1,2,3] row_mask:0xf bank_mask:0x3
	v_mov_b32_dpp v97, v26 quad_perm:[0,1,2,3] row_mask:0xf bank_mask:0x3
	v_mov_b32_dpp v25, v102 row_ror:8 row_mask:0xf bank_mask:0xf
	v_mov_b32_dpp v26, v103 row_ror:8 row_mask:0xf bank_mask:0xf
	v_mov_b32_dpp v102, v98 row_ror:8 row_mask:0xf bank_mask:0xc
	v_mov_b32_dpp v103, v99 row_ror:8 row_mask:0xf bank_mask:0xc
	v_mov_b32_dpp v98, v25 quad_perm:[0,1,2,3] row_mask:0xf bank_mask:0x3
	v_mov_b32_dpp v99, v26 quad_perm:[0,1,2,3] row_mask:0xf bank_mask:0x3
	v_mov_b32_dpp v25, v92 row_ror:8 row_mask:0xf bank_mask:0xf
	v_mov_b32_dpp v26, v93 row_ror:8 row_mask:0xf bank_mask:0xf
	v_mov_b32_dpp v92, v88 row_ror:8 row_mask:0xf bank_mask:0xc
	v_mov_b32_dpp v93, v89 row_ror:8 row_mask:0xf bank_mask:0xc
	v_mov_b32_dpp v88, v25 quad_perm:[0,1,2,3] row_mask:0xf bank_mask:0x3
	v_mov_b32_dpp v89, v26 quad_perm:[0,1,2,3] row_mask:0xf bank_mask:0x3
	v_mov_b32_dpp v25, v94 row_ror:8 row_mask:0xf bank_mask:0xf
	v_mov_b32_dpp v26, v95 row_ror:8 row_mask:0xf bank_mask:0xf
	v_mov_b32_dpp v94, v90 row_ror:8 row_mask:0xf bank_mask:0xc
	v_mov_b32_dpp v95, v91 row_ror:8 row_mask:0xf bank_mask:0xc
	v_mov_b32_dpp v90, v25 quad_perm:[0,1,2,3] row_mask:0xf bank_mask:0x3
	v_mov_b32_dpp v91, v26 quad_perm:[0,1,2,3] row_mask:0xf bank_mask:0x3
	v_mov_b32_dpp v25, v84 row_ror:8 row_mask:0xf bank_mask:0xf
	v_mov_b32_dpp v26, v85 row_ror:8 row_mask:0xf bank_mask:0xf
	v_mov_b32_dpp v84, v80 row_ror:8 row_mask:0xf bank_mask:0xc
	v_mov_b32_dpp v85, v81 row_ror:8 row_mask:0xf bank_mask:0xc
	v_mov_b32_dpp v80, v25 quad_perm:[0,1,2,3] row_mask:0xf bank_mask:0x3
	v_mov_b32_dpp v81, v26 quad_perm:[0,1,2,3] row_mask:0xf bank_mask:0x3
	v_mov_b32_dpp v25, v86 row_ror:8 row_mask:0xf bank_mask:0xf
	v_mov_b32_dpp v26, v87 row_ror:8 row_mask:0xf bank_mask:0xf
	v_mov_b32_dpp v86, v82 row_ror:8 row_mask:0xf bank_mask:0xc
	v_mov_b32_dpp v87, v83 row_ror:8 row_mask:0xf bank_mask:0xc
	v_mov_b32_dpp v82, v25 quad_perm:[0,1,2,3] row_mask:0xf bank_mask:0x3
	v_mov_b32_dpp v83, v26 quad_perm:[0,1,2,3] row_mask:0xf bank_mask:0x3
	v_mov_b32_dpp v25, v76 row_ror:8 row_mask:0xf bank_mask:0xf
	v_mov_b32_dpp v26, v77 row_ror:8 row_mask:0xf bank_mask:0xf
	v_mov_b32_dpp v76, v72 row_ror:8 row_mask:0xf bank_mask:0xc
	v_mov_b32_dpp v77, v73 row_ror:8 row_mask:0xf bank_mask:0xc
	v_mov_b32_dpp v72, v25 quad_perm:[0,1,2,3] row_mask:0xf bank_mask:0x3
	v_mov_b32_dpp v73, v26 quad_perm:[0,1,2,3] row_mask:0xf bank_mask:0x3
	v_mov_b32_dpp v25, v78 row_ror:8 row_mask:0xf bank_mask:0xf
	v_mov_b32_dpp v26, v79 row_ror:8 row_mask:0xf bank_mask:0xf
	v_mov_b32_dpp v78, v74 row_ror:8 row_mask:0xf bank_mask:0xc
	v_mov_b32_dpp v79, v75 row_ror:8 row_mask:0xf bank_mask:0xc
	v_mov_b32_dpp v74, v25 quad_perm:[0,1,2,3] row_mask:0xf bank_mask:0x3
	v_mov_b32_dpp v75, v26 quad_perm:[0,1,2,3] row_mask:0xf bank_mask:0x3
	v_mov_b32_dpp v25, v68 row_ror:8 row_mask:0xf bank_mask:0xf
	v_mov_b32_dpp v26, v69 row_ror:8 row_mask:0xf bank_mask:0xf
	v_mov_b32_dpp v68, v64 row_ror:8 row_mask:0xf bank_mask:0xc
	v_mov_b32_dpp v69, v65 row_ror:8 row_mask:0xf bank_mask:0xc
	v_mov_b32_dpp v64, v25 quad_perm:[0,1,2,3] row_mask:0xf bank_mask:0x3
	v_mov_b32_dpp v65, v26 quad_perm:[0,1,2,3] row_mask:0xf bank_mask:0x3
	v_mov_b32_dpp v25, v70 row_ror:8 row_mask:0xf bank_mask:0xf
	v_mov_b32_dpp v26, v71 row_ror:8 row_mask:0xf bank_mask:0xf
	v_mov_b32_dpp v70, v66 row_ror:8 row_mask:0xf bank_mask:0xc
	v_mov_b32_dpp v71, v67 row_ror:8 row_mask:0xf bank_mask:0xc
	v_mov_b32_dpp v66, v25 quad_perm:[0,1,2,3] row_mask:0xf bank_mask:0x3
	v_mov_b32_dpp v67, v26 quad_perm:[0,1,2,3] row_mask:0xf bank_mask:0x3
	v_mov_b32_dpp v25, v60 row_ror:8 row_mask:0xf bank_mask:0xf
	v_mov_b32_dpp v26, v61 row_ror:8 row_mask:0xf bank_mask:0xf
	v_mov_b32_dpp v60, v56 row_ror:8 row_mask:0xf bank_mask:0xc
	v_mov_b32_dpp v61, v57 row_ror:8 row_mask:0xf bank_mask:0xc
	v_mov_b32_dpp v56, v25 quad_perm:[0,1,2,3] row_mask:0xf bank_mask:0x3
	v_mov_b32_dpp v57, v26 quad_perm:[0,1,2,3] row_mask:0xf bank_mask:0x3
	v_mov_b32_dpp v25, v62 row_ror:8 row_mask:0xf bank_mask:0xf
	v_mov_b32_dpp v26, v63 row_ror:8 row_mask:0xf bank_mask:0xf
	v_mov_b32_dpp v62, v58 row_ror:8 row_mask:0xf bank_mask:0xc
	v_mov_b32_dpp v63, v59 row_ror:8 row_mask:0xf bank_mask:0xc
	v_mov_b32_dpp v58, v25 quad_perm:[0,1,2,3] row_mask:0xf bank_mask:0x3
	v_mov_b32_dpp v59, v26 quad_perm:[0,1,2,3] row_mask:0xf bank_mask:0x3
	v_mov_b32_dpp v25, v44 row_ror:8 row_mask:0xf bank_mask:0xf
	v_mov_b32_dpp v26, v45 row_ror:8 row_mask:0xf bank_mask:0xf
	v_mov_b32_dpp v44, v40 row_ror:8 row_mask:0xf bank_mask:0xc
	v_mov_b32_dpp v45, v41 row_ror:8 row_mask:0xf bank_mask:0xc
	v_mov_b32_dpp v40, v25 quad_perm:[0,1,2,3] row_mask:0xf bank_mask:0x3
	v_mov_b32_dpp v41, v26 quad_perm:[0,1,2,3] row_mask:0xf bank_mask:0x3
	v_mov_b32_dpp v25, v46 row_ror:8 row_mask:0xf bank_mask:0xf
	v_mov_b32_dpp v26, v47 row_ror:8 row_mask:0xf bank_mask:0xf
	v_mov_b32_dpp v46, v42 row_ror:8 row_mask:0xf bank_mask:0xc
	v_mov_b32_dpp v47, v43 row_ror:8 row_mask:0xf bank_mask:0xc
	v_mov_b32_dpp v42, v25 quad_perm:[0,1,2,3] row_mask:0xf bank_mask:0x3
	v_mov_b32_dpp v43, v26 quad_perm:[0,1,2,3] row_mask:0xf bank_mask:0x3
	v_mov_b32_dpp v25, v36 row_ror:8 row_mask:0xf bank_mask:0xf
	v_mov_b32_dpp v26, v37 row_ror:8 row_mask:0xf bank_mask:0xf
	v_mov_b32_dpp v36, v32 row_ror:8 row_mask:0xf bank_mask:0xc
	v_mov_b32_dpp v37, v33 row_ror:8 row_mask:0xf bank_mask:0xc
	v_mov_b32_dpp v32, v25 quad_perm:[0,1,2,3] row_mask:0xf bank_mask:0x3
; __device__ __forceinline__ unsigned cvt_pk_bf16(float lo, float hi) { unsigned r; asm volatile("v_cvt_pk_bf16_f32 %0, %1, %2" : "=v"(r) : "v"(lo), "v"(hi)); return r; }
;     __device__ __forceinline__ void operator()(const f32x4 (&acc)[2][2][4][2], const Unit& u, int wr, int wc, int fr, int fq, LAS unsigned char* lds) const {
;     ...
;                 for (int bj = 0; bj < 2; ++bj) { const size_t o = ro + bj * HALF;
;                     const f32x4 r0 = *(const f32x4*)(res + o), r1 = *(const f32x4*)(res + o + 4);
;                     const f32x4 x0 = r0 + acc[ai][bj][m][0], x1 = r1 + acc[ai][bj][m][1];
;                     *(f32x4*)(O + o) = x0; *(f32x4*)(O + o + 4) = x1;
;                     u32x4 hb; hb.x = cvt_pk_bf16(x0[0] * gg[bj][0][0], x0[1] * gg[bj][0][1]); hb.y = cvt_pk_bf16(x0[2] * gg[bj][0][2], x0[3] * gg[bj][0][3]);
;                     hb.z = cvt_pk_bf16(x1[0] * gg[bj][1][0], x1[1] * gg[bj][1][1]); hb.w = cvt_pk_bf16(x1[2] * gg[bj][1][2], x1[3] * gg[bj][1][3]);
;                     *(u32x4*)(H + o) = hb;
;                     ssq += ((x0[0] * x0[0] + x0[1] * x0[1]) + (x0[2] * x0[2] + x0[3] * x0[3])) + ((x1[0] * x1[0] + x1[1] * x1[1]) + (x1[2] * x1[2] + x1[3] * x1[3])); }
;                 ssq += __shfl_xor(ssq, 16); ssq += __shfl_xor(ssq, 32);
;                 if (fq == 0) part[(ai * HALF + wr * 64 + m * 16 + fr) * 4 + wc] = ssq; }
	v_mov_b32_dpp v33, v26 quad_perm:[0,1,2,3] row_mask:0xf bank_mask:0x3
	v_mov_b32_dpp v25, v38 row_ror:8 row_mask:0xf bank_mask:0xf
	v_mov_b32_dpp v26, v39 row_ror:8 row_mask:0xf bank_mask:0xf
	v_mov_b32_dpp v38, v34 row_ror:8 row_mask:0xf bank_mask:0xc
	v_mov_b32_dpp v39, v35 row_ror:8 row_mask:0xf bank_mask:0xc
	v_mov_b32_dpp v34, v25 quad_perm:[0,1,2,3] row_mask:0xf bank_mask:0x3
	v_mov_b32_dpp v35, v26 quad_perm:[0,1,2,3] row_mask:0xf bank_mask:0x3
	v_mov_b32_dpp v25, v20 row_ror:8 row_mask:0xf bank_mask:0xf
	v_mov_b32_dpp v26, v21 row_ror:8 row_mask:0xf bank_mask:0xf
	v_mov_b32_dpp v20, v16 row_ror:8 row_mask:0xf bank_mask:0xc
	v_mov_b32_dpp v21, v17 row_ror:8 row_mask:0xf bank_mask:0xc
	v_mov_b32_dpp v16, v25 quad_perm:[0,1,2,3] row_mask:0xf bank_mask:0x3
	v_mov_b32_dpp v17, v26 quad_perm:[0,1,2,3] row_mask:0xf bank_mask:0x3
	v_mov_b32_dpp v25, v22 row_ror:8 row_mask:0xf bank_mask:0xf
	v_mov_b32_dpp v26, v23 row_ror:8 row_mask:0xf bank_mask:0xf
	v_mov_b32_dpp v22, v18 row_ror:8 row_mask:0xf bank_mask:0xc
	v_mov_b32_dpp v23, v19 row_ror:8 row_mask:0xf bank_mask:0xc
	v_mov_b32_dpp v18, v25 quad_perm:[0,1,2,3] row_mask:0xf bank_mask:0x3
	v_mov_b32_dpp v19, v26 quad_perm:[0,1,2,3] row_mask:0xf bank_mask:0x3
	v_mov_b32_dpp v25, v12 row_ror:8 row_mask:0xf bank_mask:0xf
	v_mov_b32_dpp v26, v13 row_ror:8 row_mask:0xf bank_mask:0xf
	v_mov_b32_dpp v12, v8 row_ror:8 row_mask:0xf bank_mask:0xc
	v_mov_b32_dpp v13, v9 row_ror:8 row_mask:0xf bank_mask:0xc
	v_mov_b32_dpp v8, v25 quad_perm:[0,1,2,3] row_mask:0xf bank_mask:0x3
	v_mov_b32_dpp v9, v26 quad_perm:[0,1,2,3] row_mask:0xf bank_mask:0x3
	v_mov_b32_dpp v25, v14 row_ror:8 row_mask:0xf bank_mask:0xf
	v_mov_b32_dpp v26, v15 row_ror:8 row_mask:0xf bank_mask:0xf
	v_mov_b32_dpp v14, v10 row_ror:8 row_mask:0xf bank_mask:0xc
	v_mov_b32_dpp v15, v11 row_ror:8 row_mask:0xf bank_mask:0xc
	v_mov_b32_dpp v10, v25 quad_perm:[0,1,2,3] row_mask:0xf bank_mask:0x3
	v_mov_b32_dpp v11, v26 quad_perm:[0,1,2,3] row_mask:0xf bank_mask:0x3
	v_mov_b32_dpp v25, v4 row_ror:8 row_mask:0xf bank_mask:0xf
	v_mov_b32_dpp v26, v5 row_ror:8 row_mask:0xf bank_mask:0xf
	v_mov_b32_dpp v4, v0 row_ror:8 row_mask:0xf bank_mask:0xc
	v_mov_b32_dpp v5, v1 row_ror:8 row_mask:0xf bank_mask:0xc
	v_mov_b32_dpp v0, v25 quad_perm:[0,1,2,3] row_mask:0xf bank_mask:0x3
	v_mov_b32_dpp v1, v26 quad_perm:[0,1,2,3] row_mask:0xf bank_mask:0x3
	v_mov_b32_dpp v25, v6 row_ror:8 row_mask:0xf bank_mask:0xf
	v_mov_b32_dpp v26, v7 row_ror:8 row_mask:0xf bank_mask:0xf
	v_mov_b32_dpp v6, v2 row_ror:8 row_mask:0xf bank_mask:0xc
	v_mov_b32_dpp v7, v3 row_ror:8 row_mask:0xf bank_mask:0xc
	v_mov_b32_dpp v2, v25 quad_perm:[0,1,2,3] row_mask:0xf bank_mask:0x3
	v_mov_b32_dpp v3, v26 quad_perm:[0,1,2,3] row_mask:0xf bank_mask:0x3
	s_waitcnt vmcnt(8)
	v_pk_add_f32 v[140:141], v[140:141], v[196:197]
	v_pk_add_f32 v[142:143], v[142:143], v[198:199]
	v_pk_add_f32 v[132:133], v[132:133], v[200:201]
	v_pk_add_f32 v[134:135], v[134:135], v[202:203]
	v_pk_add_f32 v[136:137], v[136:137], v[204:205]
	v_pk_add_f32 v[138:139], v[138:139], v[206:207]
	v_pk_add_f32 v[128:129], v[128:129], v[208:209]
	v_pk_add_f32 v[130:131], v[130:131], v[210:211]
	global_store_dwordx4 v177, v[140:143], s[76:77] nt
	global_store_dwordx4 v177, v[132:135], s[76:77] offset:512 nt
	global_store_dwordx4 v195, v[136:139], s[76:77] nt
	global_store_dwordx4 v195, v[128:131], s[76:77] offset:512 nt
	global_load_dwordx4 v[196:199], v170, s[80:81] nt
	global_load_dwordx4 v[200:203], v170, s[80:81] offset:512 nt
	global_load_dwordx4 v[204:207], v171, s[80:81] nt
	global_load_dwordx4 v[208:211], v171, s[80:81] offset:512 nt
	v_add_u32_e32 v170, 0x50000, v170
	v_add_u32_e32 v171, 0x50000, v171
	v_mul_f32_e32 v27, v180, v140
	v_mul_f32_e32 v28, v181, v141
	v_cvt_pk_bf16_f32 v30, v27, v28
	v_mul_f32_e32 v27, v182, v142
	v_mul_f32_e32 v28, v183, v143
	v_cvt_pk_bf16_f32 v31, v27, v28
	global_store_dwordx2 v247, v[30:31], s[88:89]
	v_mul_f32_e32 v27, v166, v132
	v_mul_f32_e32 v28, v167, v133
	v_cvt_pk_bf16_f32 v48, v27, v28
	v_mul_f32_e32 v27, v168, v134
	v_mul_f32_e32 v28, v169, v135
	v_cvt_pk_bf16_f32 v49, v27, v28
	global_store_dwordx2 v247, v[48:49], s[88:89] offset:256
	v_mul_f32_e32 v27, v180, v136
	v_mul_f32_e32 v28, v181, v137
	v_cvt_pk_bf16_f32 v30, v27, v28
	v_mul_f32_e32 v27, v182, v138
	v_mul_f32_e32 v28, v183, v139
	v_cvt_pk_bf16_f32 v31, v27, v28
	global_store_dwordx2 v24, v[30:31], s[88:89]
	v_mul_f32_e32 v27, v166, v128
	v_mul_f32_e32 v28, v167, v129
	v_cvt_pk_bf16_f32 v48, v27, v28
	v_mul_f32_e32 v27, v168, v130
	v_mul_f32_e32 v28, v169, v131
	v_cvt_pk_bf16_f32 v49, v27, v28
	global_store_dwordx2 v24, v[48:49], s[88:89] offset:256
	v_mul_f32_e32 v50, v141, v141
	v_mul_f32_e32 v29, v143, v143
	v_fmac_f32_e32 v50, v140, v140
	v_fmac_f32_e32 v29, v142, v142
	v_add_f32_e32 v50, v50, v29
	v_mul_f32_e32 v51, v137, v137
	v_mul_f32_e32 v29, v139, v139
	v_fmac_f32_e32 v51, v136, v136
	v_fmac_f32_e32 v29, v138, v138
	v_add_f32_e32 v51, v51, v29
	v_mul_f32_e32 v52, v133, v133
	v_mul_f32_e32 v29, v135, v135
	v_fmac_f32_e32 v52, v132, v132
	v_fmac_f32_e32 v29, v134, v134
	v_add_f32_e32 v52, v52, v29
	v_mul_f32_e32 v53, v129, v129
	v_mul_f32_e32 v29, v131, v131
	v_fmac_f32_e32 v53, v128, v128
	v_fmac_f32_e32 v29, v130, v130
	v_add_f32_e32 v53, v53, v29
	v_add_f32_dpp v27, v50, v50 row_ror:8 row_mask:0xf bank_mask:0x3
	v_add_f32_dpp v28, v52, v52 row_ror:8 row_mask:0xf bank_mask:0x3
	v_add_f32_dpp v27, v51, v51 row_ror:8 row_mask:0xf bank_mask:0xc
	v_add_f32_dpp v28, v53, v53 row_ror:8 row_mask:0xf bank_mask:0xc
	v_add_f32_e32 v27, v27, v28
	ds_bpermute_b32 v29, v54, v27
	s_waitcnt lgkmcnt(0)
; __device__ __forceinline__ unsigned cvt_pk_bf16(float lo, float hi) { unsigned r; asm volatile("v_cvt_pk_bf16_f32 %0, %1, %2" : "=v"(r) : "v"(lo), "v"(hi)); return r; }
;     __device__ __forceinline__ void operator()(const f32x4 (&acc)[2][2][4][2], const Unit& u, int wr, int wc, int fr, int fq, LAS unsigned char* lds) const {
;     ...
;                 for (int bj = 0; bj < 2; ++bj) { const size_t o = ro + bj * HALF;
;                     const f32x4 r0 = *(const f32x4*)(res + o), r1 = *(const f32x4*)(res + o + 4);
;                     const f32x4 x0 = r0 + acc[ai][bj][m][0], x1 = r1 + acc[ai][bj][m][1];
;                     *(f32x4*)(O + o) = x0; *(f32x4*)(O + o + 4) = x1;
;                     u32x4 hb; hb.x = cvt_pk_bf16(x0[0] * gg[bj][0][0], x0[1] * gg[bj][0][1]); hb.y = cvt_pk_bf16(x0[2] * gg[bj][0][2], x0[3] * gg[bj][0][3]);
;                     hb.z = cvt_pk_bf16(x1[0] * gg[bj][1][0], x1[1] * gg[bj][1][1]); hb.w = cvt_pk_bf16(x1[2] * gg[bj][1][2], x1[3] * gg[bj][1][3]);
;                     *(u32x4*)(H + o) = hb;
;                     ssq += ((x0[0] * x0[0] + x0[1] * x0[1]) + (x0[2] * x0[2] + x0[3] * x0[3])) + ((x1[0] * x1[0] + x1[1] * x1[1]) + (x1[2] * x1[2] + x1[3] * x1[3])); }
;                 ssq += __shfl_xor(ssq, 16); ssq += __shfl_xor(ssq, 32);
;                 if (fq == 0) part[(ai * HALF + wr * 64 + m * 16 + fr) * 4 + wc] = ssq; }
	v_add_f32_e32 v27, v27, v29
	ds_bpermute_b32 v29, v55, v27
	s_waitcnt lgkmcnt(0)
	v_add_f32_e32 v27, v27, v29
	s_and_saveexec_b64 s[14:15], s[42:43]
	ds_write_b32 v176, v27
	s_or_b64 exec, exec, s[14:15]
	v_add_u32_e32 v177, 0x10000, v177
	v_add_u32_e32 v195, 0x10000, v195
	v_add_u32_e32 v247, 0x8000, v247
	v_add_u32_e32 v24, 0x8000, v24
	s_waitcnt vmcnt(16)
	v_pk_add_f32 v[124:125], v[124:125], v[212:213]
	v_pk_add_f32 v[126:127], v[126:127], v[214:215]
	v_pk_add_f32 v[116:117], v[116:117], v[216:217]
	v_pk_add_f32 v[118:119], v[118:119], v[218:219]
	v_pk_add_f32 v[120:121], v[120:121], v[220:221]
	v_pk_add_f32 v[122:123], v[122:123], v[222:223]
	v_pk_add_f32 v[112:113], v[112:113], v[224:225]
	v_pk_add_f32 v[114:115], v[114:115], v[226:227]
	global_store_dwordx4 v177, v[124:127], s[76:77] nt
	global_store_dwordx4 v177, v[116:119], s[76:77] offset:512 nt
	global_store_dwordx4 v195, v[120:123], s[76:77] nt
	global_store_dwordx4 v195, v[112:115], s[76:77] offset:512 nt
	global_load_dwordx4 v[212:215], v170, s[80:81] nt
	global_load_dwordx4 v[216:219], v170, s[80:81] offset:512 nt
	global_load_dwordx4 v[220:223], v171, s[80:81] nt
	global_load_dwordx4 v[224:227], v171, s[80:81] offset:512 nt
	v_add_u32_e32 v170, 0x10000, v170
	v_add_u32_e32 v171, 0x10000, v171
	v_mul_f32_e32 v27, v180, v124
	v_mul_f32_e32 v28, v181, v125
	v_cvt_pk_bf16_f32 v30, v27, v28
	v_mul_f32_e32 v27, v182, v126
	v_mul_f32_e32 v28, v183, v127
	v_cvt_pk_bf16_f32 v31, v27, v28
	global_store_dwordx2 v247, v[30:31], s[88:89]
	v_mul_f32_e32 v27, v166, v116
	v_mul_f32_e32 v28, v167, v117
	v_cvt_pk_bf16_f32 v48, v27, v28
	v_mul_f32_e32 v27, v168, v118
	v_mul_f32_e32 v28, v169, v119
	v_cvt_pk_bf16_f32 v49, v27, v28
	global_store_dwordx2 v247, v[48:49], s[88:89] offset:256
	v_mul_f32_e32 v27, v180, v120
	v_mul_f32_e32 v28, v181, v121
	v_cvt_pk_bf16_f32 v30, v27, v28
	v_mul_f32_e32 v27, v182, v122
	v_mul_f32_e32 v28, v183, v123
	v_cvt_pk_bf16_f32 v31, v27, v28
	global_store_dwordx2 v24, v[30:31], s[88:89]
	v_mul_f32_e32 v27, v166, v112
	v_mul_f32_e32 v28, v167, v113
	v_cvt_pk_bf16_f32 v48, v27, v28
	v_mul_f32_e32 v27, v168, v114
	v_mul_f32_e32 v28, v169, v115
	v_cvt_pk_bf16_f32 v49, v27, v28
	global_store_dwordx2 v24, v[48:49], s[88:89] offset:256
	v_mul_f32_e32 v50, v125, v125
	v_mul_f32_e32 v29, v127, v127
	v_fmac_f32_e32 v50, v124, v124
	v_fmac_f32_e32 v29, v126, v126
	v_add_f32_e32 v50, v50, v29
	v_mul_f32_e32 v51, v121, v121
	v_mul_f32_e32 v29, v123, v123
	v_fmac_f32_e32 v51, v120, v120
	v_fmac_f32_e32 v29, v122, v122
	v_add_f32_e32 v51, v51, v29
	v_mul_f32_e32 v52, v117, v117
	v_mul_f32_e32 v29, v119, v119
	v_fmac_f32_e32 v52, v116, v116
	v_fmac_f32_e32 v29, v118, v118
	v_add_f32_e32 v52, v52, v29
	v_mul_f32_e32 v53, v113, v113
	v_mul_f32_e32 v29, v115, v115
	v_fmac_f32_e32 v53, v112, v112
	v_fmac_f32_e32 v29, v114, v114
	v_add_f32_e32 v53, v53, v29
	v_add_f32_dpp v27, v50, v50 row_ror:8 row_mask:0xf bank_mask:0x3
	v_add_f32_dpp v28, v52, v52 row_ror:8 row_mask:0xf bank_mask:0x3
	v_add_f32_dpp v27, v51, v51 row_ror:8 row_mask:0xf bank_mask:0xc
	v_add_f32_dpp v28, v53, v53 row_ror:8 row_mask:0xf bank_mask:0xc
	v_add_f32_e32 v27, v27, v28
	ds_bpermute_b32 v29, v54, v27
	s_waitcnt lgkmcnt(0)
	v_add_f32_e32 v27, v27, v29
	ds_bpermute_b32 v29, v55, v27
	s_waitcnt lgkmcnt(0)
	v_add_f32_e32 v27, v27, v29
	s_and_saveexec_b64 s[14:15], s[42:43]
	ds_write_b32 v176, v27 offset:256
	s_or_b64 exec, exec, s[14:15]
	v_add_u32_e32 v177, 0x10000, v177
	v_add_u32_e32 v195, 0x10000, v195
	v_add_u32_e32 v247, 0x8000, v247
	v_add_u32_e32 v24, 0x8000, v24
	s_waitcnt vmcnt(24)
	v_pk_add_f32 v[108:109], v[108:109], v[228:229]
	v_pk_add_f32 v[110:111], v[110:111], v[230:231]
	v_pk_add_f32 v[100:101], v[100:101], v[232:233]
	v_pk_add_f32 v[102:103], v[102:103], v[234:235]
	v_pk_add_f32 v[104:105], v[104:105], v[236:237]
	v_pk_add_f32 v[106:107], v[106:107], v[238:239]
	v_pk_add_f32 v[96:97], v[96:97], v[240:241]
	v_pk_add_f32 v[98:99], v[98:99], v[242:243]
	global_store_dwordx4 v177, v[108:111], s[76:77] nt
	global_store_dwordx4 v177, v[100:103], s[76:77] offset:512 nt
	global_store_dwordx4 v195, v[104:107], s[76:77] nt
	global_store_dwordx4 v195, v[96:99], s[76:77] offset:512 nt
	global_load_dwordx4 v[228:231], v170, s[80:81] nt
	global_load_dwordx4 v[232:235], v170, s[80:81] offset:512 nt
	global_load_dwordx4 v[236:239], v171, s[80:81] nt
	global_load_dwordx4 v[240:243], v171, s[80:81] offset:512 nt
	v_add_u32_e32 v170, 0x10000, v170
	v_add_u32_e32 v171, 0x10000, v171
	v_mul_f32_e32 v27, v180, v108
	v_mul_f32_e32 v28, v181, v109
	v_cvt_pk_bf16_f32 v30, v27, v28
	v_mul_f32_e32 v27, v182, v110
	v_mul_f32_e32 v28, v183, v111
	v_cvt_pk_bf16_f32 v31, v27, v28
	global_store_dwordx2 v247, v[30:31], s[88:89]
	v_mul_f32_e32 v27, v166, v100
	v_mul_f32_e32 v28, v167, v101
	v_cvt_pk_bf16_f32 v48, v27, v28
	v_mul_f32_e32 v27, v168, v102
	v_mul_f32_e32 v28, v169, v103
	v_cvt_pk_bf16_f32 v49, v27, v28
	global_store_dwordx2 v247, v[48:49], s[88:89] offset:256
	v_mul_f32_e32 v27, v180, v104
	v_mul_f32_e32 v28, v181, v105
	v_cvt_pk_bf16_f32 v30, v27, v28
	v_mul_f32_e32 v27, v182, v106
	v_mul_f32_e32 v28, v183, v107
	v_cvt_pk_bf16_f32 v31, v27, v28
	global_store_dwordx2 v24, v[30:31], s[88:89]
	v_mul_f32_e32 v27, v166, v96
	v_mul_f32_e32 v28, v167, v97
	v_cvt_pk_bf16_f32 v48, v27, v28
	v_mul_f32_e32 v27, v168, v98
	v_mul_f32_e32 v28, v169, v99
	v_cvt_pk_bf16_f32 v49, v27, v28
	global_store_dwordx2 v24, v[48:49], s[88:89] offset:256
	v_mul_f32_e32 v50, v109, v109
	v_mul_f32_e32 v29, v111, v111
	v_fmac_f32_e32 v50, v108, v108
	v_fmac_f32_e32 v29, v110, v110
	v_add_f32_e32 v50, v50, v29
	v_mul_f32_e32 v51, v105, v105
	v_mul_f32_e32 v29, v107, v107
	v_fmac_f32_e32 v51, v104, v104
	v_fmac_f32_e32 v29, v106, v106
	v_add_f32_e32 v51, v51, v29
	v_mul_f32_e32 v52, v101, v101
	v_mul_f32_e32 v29, v103, v103
	v_fmac_f32_e32 v52, v100, v100
	v_fmac_f32_e32 v29, v102, v102
	v_add_f32_e32 v52, v52, v29
	v_mul_f32_e32 v53, v97, v97
	v_mul_f32_e32 v29, v99, v99
	v_fmac_f32_e32 v53, v96, v96
	v_fmac_f32_e32 v29, v98, v98
	v_add_f32_e32 v53, v53, v29
	v_add_f32_dpp v27, v50, v50 row_ror:8 row_mask:0xf bank_mask:0x3
	v_add_f32_dpp v28, v52, v52 row_ror:8 row_mask:0xf bank_mask:0x3
	v_add_f32_dpp v27, v51, v51 row_ror:8 row_mask:0xf bank_mask:0xc
	v_add_f32_dpp v28, v53, v53 row_ror:8 row_mask:0xf bank_mask:0xc
	v_add_f32_e32 v27, v27, v28
	ds_bpermute_b32 v29, v54, v27
	s_waitcnt lgkmcnt(0)
; __device__ __forceinline__ unsigned cvt_pk_bf16(float lo, float hi) { unsigned r; asm volatile("v_cvt_pk_bf16_f32 %0, %1, %2" : "=v"(r) : "v"(lo), "v"(hi)); return r; }
;     __device__ __forceinline__ void operator()(const f32x4 (&acc)[2][2][4][2], const Unit& u, int wr, int wc, int fr, int fq, LAS unsigned char* lds) const {
;     ...
;                 for (int bj = 0; bj < 2; ++bj) { const size_t o = ro + bj * HALF;
;                     const f32x4 r0 = *(const f32x4*)(res + o), r1 = *(const f32x4*)(res + o + 4);
;                     const f32x4 x0 = r0 + acc[ai][bj][m][0], x1 = r1 + acc[ai][bj][m][1];
;                     *(f32x4*)(O + o) = x0; *(f32x4*)(O + o + 4) = x1;
;                     u32x4 hb; hb.x = cvt_pk_bf16(x0[0] * gg[bj][0][0], x0[1] * gg[bj][0][1]); hb.y = cvt_pk_bf16(x0[2] * gg[bj][0][2], x0[3] * gg[bj][0][3]);
;                     hb.z = cvt_pk_bf16(x1[0] * gg[bj][1][0], x1[1] * gg[bj][1][1]); hb.w = cvt_pk_bf16(x1[2] * gg[bj][1][2], x1[3] * gg[bj][1][3]);
;                     *(u32x4*)(H + o) = hb;
;                     ssq += ((x0[0] * x0[0] + x0[1] * x0[1]) + (x0[2] * x0[2] + x0[3] * x0[3])) + ((x1[0] * x1[0] + x1[1] * x1[1]) + (x1[2] * x1[2] + x1[3] * x1[3])); }
;                 ssq += __shfl_xor(ssq, 16); ssq += __shfl_xor(ssq, 32);
;                 if (fq == 0) part[(ai * HALF + wr * 64 + m * 16 + fr) * 4 + wc] = ssq; }
	v_add_f32_e32 v27, v27, v29
	ds_bpermute_b32 v29, v55, v27
	s_waitcnt lgkmcnt(0)
	v_add_f32_e32 v27, v27, v29
	s_and_saveexec_b64 s[14:15], s[42:43]
	ds_write_b32 v176, v27 offset:512
	s_or_b64 exec, exec, s[14:15]
	v_add_u32_e32 v177, 0x10000, v177
	v_add_u32_e32 v195, 0x10000, v195
	v_add_u32_e32 v247, 0x8000, v247
	v_add_u32_e32 v24, 0x8000, v24
	s_waitcnt vmcnt(28)
	v_pk_add_f32 v[92:93], v[92:93], v[196:197]
	v_pk_add_f32 v[94:95], v[94:95], v[198:199]
	v_pk_add_f32 v[84:85], v[84:85], v[200:201]
	v_pk_add_f32 v[86:87], v[86:87], v[202:203]
	v_pk_add_f32 v[88:89], v[88:89], v[204:205]
	v_pk_add_f32 v[90:91], v[90:91], v[206:207]
	v_pk_add_f32 v[80:81], v[80:81], v[208:209]
	v_pk_add_f32 v[82:83], v[82:83], v[210:211]
	global_store_dwordx4 v177, v[92:95], s[76:77] nt
	global_store_dwordx4 v177, v[84:87], s[76:77] offset:512 nt
	global_store_dwordx4 v195, v[88:91], s[76:77] nt
	global_store_dwordx4 v195, v[80:83], s[76:77] offset:512 nt
	global_load_dwordx4 v[196:199], v170, s[80:81] nt
	global_load_dwordx4 v[200:203], v170, s[80:81] offset:512 nt
	global_load_dwordx4 v[204:207], v171, s[80:81] nt
	global_load_dwordx4 v[208:211], v171, s[80:81] offset:512 nt
	v_add_u32_e32 v170, 0x10000, v170
	v_add_u32_e32 v171, 0x10000, v171
	v_mul_f32_e32 v27, v180, v92
	v_mul_f32_e32 v28, v181, v93
	v_cvt_pk_bf16_f32 v30, v27, v28
	v_mul_f32_e32 v27, v182, v94
	v_mul_f32_e32 v28, v183, v95
	v_cvt_pk_bf16_f32 v31, v27, v28
	global_store_dwordx2 v247, v[30:31], s[88:89]
	v_mul_f32_e32 v27, v166, v84
	v_mul_f32_e32 v28, v167, v85
	v_cvt_pk_bf16_f32 v48, v27, v28
	v_mul_f32_e32 v27, v168, v86
	v_mul_f32_e32 v28, v169, v87
	v_cvt_pk_bf16_f32 v49, v27, v28
	global_store_dwordx2 v247, v[48:49], s[88:89] offset:256
	v_mul_f32_e32 v27, v180, v88
	v_mul_f32_e32 v28, v181, v89
	v_cvt_pk_bf16_f32 v30, v27, v28
	v_mul_f32_e32 v27, v182, v90
	v_mul_f32_e32 v28, v183, v91
	v_cvt_pk_bf16_f32 v31, v27, v28
	global_store_dwordx2 v24, v[30:31], s[88:89]
	v_mul_f32_e32 v27, v166, v80
	v_mul_f32_e32 v28, v167, v81
	v_cvt_pk_bf16_f32 v48, v27, v28
	v_mul_f32_e32 v27, v168, v82
	v_mul_f32_e32 v28, v169, v83
	v_cvt_pk_bf16_f32 v49, v27, v28
	global_store_dwordx2 v24, v[48:49], s[88:89] offset:256
	v_mul_f32_e32 v50, v93, v93
	v_mul_f32_e32 v29, v95, v95
	v_fmac_f32_e32 v50, v92, v92
	v_fmac_f32_e32 v29, v94, v94
	v_add_f32_e32 v50, v50, v29
	v_mul_f32_e32 v51, v89, v89
	v_mul_f32_e32 v29, v91, v91
	v_fmac_f32_e32 v51, v88, v88
	v_fmac_f32_e32 v29, v90, v90
	v_add_f32_e32 v51, v51, v29
	v_mul_f32_e32 v52, v85, v85
	v_mul_f32_e32 v29, v87, v87
	v_fmac_f32_e32 v52, v84, v84
	v_fmac_f32_e32 v29, v86, v86
	v_add_f32_e32 v52, v52, v29
	v_mul_f32_e32 v53, v81, v81
	v_mul_f32_e32 v29, v83, v83
	v_fmac_f32_e32 v53, v80, v80
	v_fmac_f32_e32 v29, v82, v82
	v_add_f32_e32 v53, v53, v29
	v_add_f32_dpp v27, v50, v50 row_ror:8 row_mask:0xf bank_mask:0x3
	v_add_f32_dpp v28, v52, v52 row_ror:8 row_mask:0xf bank_mask:0x3
	v_add_f32_dpp v27, v51, v51 row_ror:8 row_mask:0xf bank_mask:0xc
	v_add_f32_dpp v28, v53, v53 row_ror:8 row_mask:0xf bank_mask:0xc
	v_add_f32_e32 v27, v27, v28
	ds_bpermute_b32 v29, v54, v27
	s_waitcnt lgkmcnt(0)
	v_add_f32_e32 v27, v27, v29
	ds_bpermute_b32 v29, v55, v27
	s_waitcnt lgkmcnt(0)
	v_add_f32_e32 v27, v27, v29
	s_and_saveexec_b64 s[14:15], s[42:43]
	ds_write_b32 v176, v27 offset:768
	s_or_b64 exec, exec, s[14:15]
	v_add_u32_e32 v177, 0x50000, v177
	v_add_u32_e32 v195, 0x50000, v195
	v_add_u32_e32 v247, 0x28000, v247
	v_add_u32_e32 v24, 0x28000, v24
	s_waitcnt vmcnt(28)
	v_pk_add_f32 v[76:77], v[76:77], v[212:213]
	v_pk_add_f32 v[78:79], v[78:79], v[214:215]
	v_pk_add_f32 v[68:69], v[68:69], v[216:217]
	v_pk_add_f32 v[70:71], v[70:71], v[218:219]
	v_pk_add_f32 v[72:73], v[72:73], v[220:221]
	v_pk_add_f32 v[74:75], v[74:75], v[222:223]
	v_pk_add_f32 v[64:65], v[64:65], v[224:225]
	v_pk_add_f32 v[66:67], v[66:67], v[226:227]
	global_store_dwordx4 v177, v[76:79], s[76:77] nt
	global_store_dwordx4 v177, v[68:71], s[76:77] offset:512 nt
	global_store_dwordx4 v195, v[72:75], s[76:77] nt
	global_store_dwordx4 v195, v[64:67], s[76:77] offset:512 nt
	global_load_dwordx4 v[212:215], v170, s[80:81] nt
	global_load_dwordx4 v[216:219], v170, s[80:81] offset:512 nt
	global_load_dwordx4 v[220:223], v171, s[80:81] nt
	global_load_dwordx4 v[224:227], v171, s[80:81] offset:512 nt
	v_mul_f32_e32 v27, v180, v76
	v_mul_f32_e32 v28, v181, v77
	v_cvt_pk_bf16_f32 v30, v27, v28
	v_mul_f32_e32 v27, v182, v78
	v_mul_f32_e32 v28, v183, v79
	v_cvt_pk_bf16_f32 v31, v27, v28
	global_store_dwordx2 v247, v[30:31], s[88:89]
	v_mul_f32_e32 v27, v166, v68
	v_mul_f32_e32 v28, v167, v69
	v_cvt_pk_bf16_f32 v48, v27, v28
	v_mul_f32_e32 v27, v168, v70
	v_mul_f32_e32 v28, v169, v71
	v_cvt_pk_bf16_f32 v49, v27, v28
	global_store_dwordx2 v247, v[48:49], s[88:89] offset:256
	v_mul_f32_e32 v27, v180, v72
	v_mul_f32_e32 v28, v181, v73
	v_cvt_pk_bf16_f32 v30, v27, v28
	v_mul_f32_e32 v27, v182, v74
	v_mul_f32_e32 v28, v183, v75
	v_cvt_pk_bf16_f32 v31, v27, v28
	global_store_dwordx2 v24, v[30:31], s[88:89]
	v_mul_f32_e32 v27, v166, v64
	v_mul_f32_e32 v28, v167, v65
	v_cvt_pk_bf16_f32 v48, v27, v28
	v_mul_f32_e32 v27, v168, v66
	v_mul_f32_e32 v28, v169, v67
	v_cvt_pk_bf16_f32 v49, v27, v28
	global_store_dwordx2 v24, v[48:49], s[88:89] offset:256
	v_mul_f32_e32 v50, v77, v77
	v_mul_f32_e32 v29, v79, v79
	v_fmac_f32_e32 v50, v76, v76
	v_fmac_f32_e32 v29, v78, v78
	v_add_f32_e32 v50, v50, v29
	v_mul_f32_e32 v51, v73, v73
	v_mul_f32_e32 v29, v75, v75
	v_fmac_f32_e32 v51, v72, v72
	v_fmac_f32_e32 v29, v74, v74
	v_add_f32_e32 v51, v51, v29
	v_mul_f32_e32 v52, v69, v69
	v_mul_f32_e32 v29, v71, v71
	v_fmac_f32_e32 v52, v68, v68
	v_fmac_f32_e32 v29, v70, v70
	v_add_f32_e32 v52, v52, v29
	v_mul_f32_e32 v53, v65, v65
	v_mul_f32_e32 v29, v67, v67
	v_fmac_f32_e32 v53, v64, v64
	v_fmac_f32_e32 v29, v66, v66
	v_add_f32_e32 v53, v53, v29
	v_add_f32_dpp v27, v50, v50 row_ror:8 row_mask:0xf bank_mask:0x3
	v_add_f32_dpp v28, v52, v52 row_ror:8 row_mask:0xf bank_mask:0x3
	v_add_f32_dpp v27, v51, v51 row_ror:8 row_mask:0xf bank_mask:0xc
	v_add_f32_dpp v28, v53, v53 row_ror:8 row_mask:0xf bank_mask:0xc
	v_add_f32_e32 v27, v27, v28
	ds_bpermute_b32 v29, v54, v27
	s_waitcnt lgkmcnt(0)
; __device__ __forceinline__ unsigned cvt_pk_bf16(float lo, float hi) { unsigned r; asm volatile("v_cvt_pk_bf16_f32 %0, %1, %2" : "=v"(r) : "v"(lo), "v"(hi)); return r; }
;     __device__ __forceinline__ void operator()(const f32x4 (&acc)[2][2][4][2], const Unit& u, int wr, int wc, int fr, int fq, LAS unsigned char* lds) const {
;     ...
;                 for (int bj = 0; bj < 2; ++bj) { const size_t o = ro + bj * HALF;
;                     const f32x4 r0 = *(const f32x4*)(res + o), r1 = *(const f32x4*)(res + o + 4);
;                     const f32x4 x0 = r0 + acc[ai][bj][m][0], x1 = r1 + acc[ai][bj][m][1];
;                     *(f32x4*)(O + o) = x0; *(f32x4*)(O + o + 4) = x1;
;                     u32x4 hb; hb.x = cvt_pk_bf16(x0[0] * gg[bj][0][0], x0[1] * gg[bj][0][1]); hb.y = cvt_pk_bf16(x0[2] * gg[bj][0][2], x0[3] * gg[bj][0][3]);
;                     hb.z = cvt_pk_bf16(x1[0] * gg[bj][1][0], x1[1] * gg[bj][1][1]); hb.w = cvt_pk_bf16(x1[2] * gg[bj][1][2], x1[3] * gg[bj][1][3]);
;                     *(u32x4*)(H + o) = hb;
;                     ssq += ((x0[0] * x0[0] + x0[1] * x0[1]) + (x0[2] * x0[2] + x0[3] * x0[3])) + ((x1[0] * x1[0] + x1[1] * x1[1]) + (x1[2] * x1[2] + x1[3] * x1[3])); }
;                 ssq += __shfl_xor(ssq, 16); ssq += __shfl_xor(ssq, 32);
;                 if (fq == 0) part[(ai * HALF + wr * 64 + m * 16 + fr) * 4 + wc] = ssq; }
	v_add_f32_e32 v27, v27, v29
	ds_bpermute_b32 v29, v55, v27
	s_waitcnt lgkmcnt(0)
	v_add_f32_e32 v27, v27, v29
	s_and_saveexec_b64 s[14:15], s[42:43]
	ds_write_b32 v176, v27 offset:2048
	s_or_b64 exec, exec, s[14:15]
	v_add_u32_e32 v177, 0x10000, v177
	v_add_u32_e32 v195, 0x10000, v195
	v_add_u32_e32 v247, 0x8000, v247
	v_add_u32_e32 v24, 0x8000, v24
	s_waitcnt vmcnt(28)
	v_pk_add_f32 v[60:61], v[60:61], v[228:229]
	v_pk_add_f32 v[62:63], v[62:63], v[230:231]
	v_pk_add_f32 v[44:45], v[44:45], v[232:233]
	v_pk_add_f32 v[46:47], v[46:47], v[234:235]
	v_pk_add_f32 v[56:57], v[56:57], v[236:237]
	v_pk_add_f32 v[58:59], v[58:59], v[238:239]
	v_pk_add_f32 v[40:41], v[40:41], v[240:241]
	v_pk_add_f32 v[42:43], v[42:43], v[242:243]
	global_store_dwordx4 v177, v[60:63], s[76:77] nt
	global_store_dwordx4 v177, v[44:47], s[76:77] offset:512 nt
	global_store_dwordx4 v195, v[56:59], s[76:77] nt
	global_store_dwordx4 v195, v[40:43], s[76:77] offset:512 nt
	v_mul_f32_e32 v27, v180, v60
	v_mul_f32_e32 v28, v181, v61
	v_cvt_pk_bf16_f32 v30, v27, v28
	v_mul_f32_e32 v27, v182, v62
	v_mul_f32_e32 v28, v183, v63
	v_cvt_pk_bf16_f32 v31, v27, v28
	global_store_dwordx2 v247, v[30:31], s[88:89]
	v_mul_f32_e32 v27, v166, v44
	v_mul_f32_e32 v28, v167, v45
	v_cvt_pk_bf16_f32 v48, v27, v28
	v_mul_f32_e32 v27, v168, v46
	v_mul_f32_e32 v28, v169, v47
	v_cvt_pk_bf16_f32 v49, v27, v28
	global_store_dwordx2 v247, v[48:49], s[88:89] offset:256
	v_mul_f32_e32 v27, v180, v56
	v_mul_f32_e32 v28, v181, v57
	v_cvt_pk_bf16_f32 v30, v27, v28
	v_mul_f32_e32 v27, v182, v58
	v_mul_f32_e32 v28, v183, v59
	v_cvt_pk_bf16_f32 v31, v27, v28
	global_store_dwordx2 v24, v[30:31], s[88:89]
	v_mul_f32_e32 v27, v166, v40
	v_mul_f32_e32 v28, v167, v41
	v_cvt_pk_bf16_f32 v48, v27, v28
	v_mul_f32_e32 v27, v168, v42
	v_mul_f32_e32 v28, v169, v43
	v_cvt_pk_bf16_f32 v49, v27, v28
	global_store_dwordx2 v24, v[48:49], s[88:89] offset:256
	v_mul_f32_e32 v50, v61, v61
	v_mul_f32_e32 v29, v63, v63
	v_fmac_f32_e32 v50, v60, v60
	v_fmac_f32_e32 v29, v62, v62
	v_add_f32_e32 v50, v50, v29
	v_mul_f32_e32 v51, v57, v57
	v_mul_f32_e32 v29, v59, v59
	v_fmac_f32_e32 v51, v56, v56
	v_fmac_f32_e32 v29, v58, v58
	v_add_f32_e32 v51, v51, v29
	v_mul_f32_e32 v52, v45, v45
	v_mul_f32_e32 v29, v47, v47
	v_fmac_f32_e32 v52, v44, v44
	v_fmac_f32_e32 v29, v46, v46
	v_add_f32_e32 v52, v52, v29
	v_mul_f32_e32 v53, v41, v41
	v_mul_f32_e32 v29, v43, v43
	v_fmac_f32_e32 v53, v40, v40
	v_fmac_f32_e32 v29, v42, v42
	v_add_f32_e32 v53, v53, v29
	v_add_f32_dpp v27, v50, v50 row_ror:8 row_mask:0xf bank_mask:0x3
	v_add_f32_dpp v28, v52, v52 row_ror:8 row_mask:0xf bank_mask:0x3
	v_add_f32_dpp v27, v51, v51 row_ror:8 row_mask:0xf bank_mask:0xc
	v_add_f32_dpp v28, v53, v53 row_ror:8 row_mask:0xf bank_mask:0xc
	v_add_f32_e32 v27, v27, v28
	ds_bpermute_b32 v29, v54, v27
	s_waitcnt lgkmcnt(0)
	v_add_f32_e32 v27, v27, v29
	ds_bpermute_b32 v29, v55, v27
	s_waitcnt lgkmcnt(0)
	v_add_f32_e32 v27, v27, v29
	s_and_saveexec_b64 s[14:15], s[42:43]
	ds_write_b32 v176, v27 offset:2304
	s_or_b64 exec, exec, s[14:15]
	v_add_u32_e32 v177, 0x10000, v177
	v_add_u32_e32 v195, 0x10000, v195
	v_add_u32_e32 v247, 0x8000, v247
	v_add_u32_e32 v24, 0x8000, v24
	s_waitcnt vmcnt(24)
	v_pk_add_f32 v[36:37], v[36:37], v[196:197]
	v_pk_add_f32 v[38:39], v[38:39], v[198:199]
	v_pk_add_f32 v[20:21], v[20:21], v[200:201]
	v_pk_add_f32 v[22:23], v[22:23], v[202:203]
	v_pk_add_f32 v[32:33], v[32:33], v[204:205]
	v_pk_add_f32 v[34:35], v[34:35], v[206:207]
	v_pk_add_f32 v[16:17], v[16:17], v[208:209]
	v_pk_add_f32 v[18:19], v[18:19], v[210:211]
	global_store_dwordx4 v177, v[36:39], s[76:77] nt
	global_store_dwordx4 v177, v[20:23], s[76:77] offset:512 nt
	global_store_dwordx4 v195, v[32:35], s[76:77] nt
	global_store_dwordx4 v195, v[16:19], s[76:77] offset:512 nt
	v_mul_f32_e32 v27, v180, v36
	v_mul_f32_e32 v28, v181, v37
	v_cvt_pk_bf16_f32 v30, v27, v28
	v_mul_f32_e32 v27, v182, v38
	v_mul_f32_e32 v28, v183, v39
	v_cvt_pk_bf16_f32 v31, v27, v28
	global_store_dwordx2 v247, v[30:31], s[88:89]
	v_mul_f32_e32 v27, v166, v20
	v_mul_f32_e32 v28, v167, v21
	v_cvt_pk_bf16_f32 v48, v27, v28
	v_mul_f32_e32 v27, v168, v22
	v_mul_f32_e32 v28, v169, v23
	v_cvt_pk_bf16_f32 v49, v27, v28
	global_store_dwordx2 v247, v[48:49], s[88:89] offset:256
	v_mul_f32_e32 v27, v180, v32
	v_mul_f32_e32 v28, v181, v33
	v_cvt_pk_bf16_f32 v30, v27, v28
	v_mul_f32_e32 v27, v182, v34
	v_mul_f32_e32 v28, v183, v35
	v_cvt_pk_bf16_f32 v31, v27, v28
	global_store_dwordx2 v24, v[30:31], s[88:89]
	v_mul_f32_e32 v27, v166, v16
	v_mul_f32_e32 v28, v167, v17
	v_cvt_pk_bf16_f32 v48, v27, v28
	v_mul_f32_e32 v27, v168, v18
	v_mul_f32_e32 v28, v169, v19
	v_cvt_pk_bf16_f32 v49, v27, v28
	global_store_dwordx2 v24, v[48:49], s[88:89] offset:256
	v_mul_f32_e32 v50, v37, v37
	v_mul_f32_e32 v29, v39, v39
	v_fmac_f32_e32 v50, v36, v36
	v_fmac_f32_e32 v29, v38, v38
	v_add_f32_e32 v50, v50, v29
	v_mul_f32_e32 v51, v33, v33
	v_mul_f32_e32 v29, v35, v35
	v_fmac_f32_e32 v51, v32, v32
	v_fmac_f32_e32 v29, v34, v34
	v_add_f32_e32 v51, v51, v29
	v_mul_f32_e32 v52, v21, v21
	v_mul_f32_e32 v29, v23, v23
	v_fmac_f32_e32 v52, v20, v20
	v_fmac_f32_e32 v29, v22, v22
	v_add_f32_e32 v52, v52, v29
	v_mul_f32_e32 v53, v17, v17
	v_mul_f32_e32 v29, v19, v19
	v_fmac_f32_e32 v53, v16, v16
	v_fmac_f32_e32 v29, v18, v18
	v_add_f32_e32 v53, v53, v29
	v_add_f32_dpp v27, v50, v50 row_ror:8 row_mask:0xf bank_mask:0x3
	v_add_f32_dpp v28, v52, v52 row_ror:8 row_mask:0xf bank_mask:0x3
	v_add_f32_dpp v27, v51, v51 row_ror:8 row_mask:0xf bank_mask:0xc
	v_add_f32_dpp v28, v53, v53 row_ror:8 row_mask:0xf bank_mask:0xc
	v_add_f32_e32 v27, v27, v28
	ds_bpermute_b32 v29, v54, v27
	s_waitcnt lgkmcnt(0)
; #define LAS __attribute__((address_space(3)))
; __device__ __forceinline__ unsigned cvt_pk_bf16(float lo, float hi) { unsigned r; asm volatile("v_cvt_pk_bf16_f32 %0, %1, %2" : "=v"(r) : "v"(lo), "v"(hi)); return r; }
;     __device__ __forceinline__ void operator()(const f32x4 (&acc)[2][2][4][2], const Unit& u, int wr, int wc, int fr, int fq, LAS unsigned char* lds) const {
;     ...
;                 for (int bj = 0; bj < 2; ++bj) { const size_t o = ro + bj * HALF;
;                     const f32x4 r0 = *(const f32x4*)(res + o), r1 = *(const f32x4*)(res + o + 4);
;                     const f32x4 x0 = r0 + acc[ai][bj][m][0], x1 = r1 + acc[ai][bj][m][1];
;                     *(f32x4*)(O + o) = x0; *(f32x4*)(O + o + 4) = x1;
;                     u32x4 hb; hb.x = cvt_pk_bf16(x0[0] * gg[bj][0][0], x0[1] * gg[bj][0][1]); hb.y = cvt_pk_bf16(x0[2] * gg[bj][0][2], x0[3] * gg[bj][0][3]);
;                     hb.z = cvt_pk_bf16(x1[0] * gg[bj][1][0], x1[1] * gg[bj][1][1]); hb.w = cvt_pk_bf16(x1[2] * gg[bj][1][2], x1[3] * gg[bj][1][3]);
;                     *(u32x4*)(H + o) = hb;
;                     ssq += ((x0[0] * x0[0] + x0[1] * x0[1]) + (x0[2] * x0[2] + x0[3] * x0[3])) + ((x1[0] * x1[0] + x1[1] * x1[1]) + (x1[2] * x1[2] + x1[3] * x1[3])); }
;                 ssq += __shfl_xor(ssq, 16); ssq += __shfl_xor(ssq, 32);
;                 if (fq == 0) part[(ai * HALF + wr * 64 + m * 16 + fr) * 4 + wc] = ssq; }
;         asm volatile("s_waitcnt lgkmcnt(0)" ::: "memory"); __builtin_amdgcn_s_barrier(); asm volatile("" ::: "memory");
;         const int t = threadIdx.x;
;         if (t < 256) { const f32x4 p = *(const LAS f32x4*)(part + t * 4); rss[(size_t)u.pn * NTOK + u.pm * BM + t] = (p[0] + p[1]) + (p[2] + p[3]); }
	v_add_f32_e32 v27, v27, v29
	ds_bpermute_b32 v29, v55, v27
	s_waitcnt lgkmcnt(0)
	v_add_f32_e32 v27, v27, v29
	s_and_saveexec_b64 s[14:15], s[42:43]
	ds_write_b32 v176, v27 offset:2560
	s_or_b64 exec, exec, s[14:15]
	v_add_u32_e32 v177, 0x10000, v177
	v_add_u32_e32 v195, 0x10000, v195
	v_add_u32_e32 v247, 0x8000, v247
	v_add_u32_e32 v24, 0x8000, v24
	s_waitcnt vmcnt(20)
	v_pk_add_f32 v[12:13], v[12:13], v[212:213]
	v_pk_add_f32 v[14:15], v[14:15], v[214:215]
	v_pk_add_f32 v[4:5], v[4:5], v[216:217]
	v_pk_add_f32 v[6:7], v[6:7], v[218:219]
	v_pk_add_f32 v[8:9], v[8:9], v[220:221]
	v_pk_add_f32 v[10:11], v[10:11], v[222:223]
	v_pk_add_f32 v[0:1], v[0:1], v[224:225]
	v_pk_add_f32 v[2:3], v[2:3], v[226:227]
	global_store_dwordx4 v177, v[12:15], s[76:77] nt
	global_store_dwordx4 v177, v[4:7], s[76:77] offset:512 nt
	global_store_dwordx4 v195, v[8:11], s[76:77] nt
	global_store_dwordx4 v195, v[0:3], s[76:77] offset:512 nt
	v_mul_f32_e32 v27, v180, v12
	v_mul_f32_e32 v28, v181, v13
	v_cvt_pk_bf16_f32 v30, v27, v28
	v_mul_f32_e32 v27, v182, v14
	v_mul_f32_e32 v28, v183, v15
	v_cvt_pk_bf16_f32 v31, v27, v28
	global_store_dwordx2 v247, v[30:31], s[88:89]
	v_mul_f32_e32 v27, v166, v4
	v_mul_f32_e32 v28, v167, v5
	v_cvt_pk_bf16_f32 v48, v27, v28
	v_mul_f32_e32 v27, v168, v6
	v_mul_f32_e32 v28, v169, v7
	v_cvt_pk_bf16_f32 v49, v27, v28
	global_store_dwordx2 v247, v[48:49], s[88:89] offset:256
	v_mul_f32_e32 v27, v180, v8
	v_mul_f32_e32 v28, v181, v9
	v_cvt_pk_bf16_f32 v30, v27, v28
	v_mul_f32_e32 v27, v182, v10
	v_mul_f32_e32 v28, v183, v11
	v_cvt_pk_bf16_f32 v31, v27, v28
	global_store_dwordx2 v24, v[30:31], s[88:89]
	v_mul_f32_e32 v27, v166, v0
	v_mul_f32_e32 v28, v167, v1
	v_cvt_pk_bf16_f32 v48, v27, v28
	v_mul_f32_e32 v27, v168, v2
	v_mul_f32_e32 v28, v169, v3
	v_cvt_pk_bf16_f32 v49, v27, v28
	global_store_dwordx2 v24, v[48:49], s[88:89] offset:256
	v_mul_f32_e32 v50, v13, v13
	v_mul_f32_e32 v29, v15, v15
	v_fmac_f32_e32 v50, v12, v12
	v_fmac_f32_e32 v29, v14, v14
	v_add_f32_e32 v50, v50, v29
	v_mul_f32_e32 v51, v9, v9
	v_mul_f32_e32 v29, v11, v11
	v_fmac_f32_e32 v51, v8, v8
	v_fmac_f32_e32 v29, v10, v10
	v_add_f32_e32 v51, v51, v29
	v_mul_f32_e32 v52, v5, v5
	v_mul_f32_e32 v29, v7, v7
	v_fmac_f32_e32 v52, v4, v4
	v_fmac_f32_e32 v29, v6, v6
	v_add_f32_e32 v52, v52, v29
	v_mul_f32_e32 v53, v1, v1
	v_mul_f32_e32 v29, v3, v3
	v_fmac_f32_e32 v53, v0, v0
	v_fmac_f32_e32 v29, v2, v2
	v_add_f32_e32 v53, v53, v29
	v_add_f32_dpp v27, v50, v50 row_ror:8 row_mask:0xf bank_mask:0x3
	v_add_f32_dpp v28, v52, v52 row_ror:8 row_mask:0xf bank_mask:0x3
	v_add_f32_dpp v27, v51, v51 row_ror:8 row_mask:0xf bank_mask:0xc
	v_add_f32_dpp v28, v53, v53 row_ror:8 row_mask:0xf bank_mask:0xc
	v_add_f32_e32 v27, v27, v28
	ds_bpermute_b32 v29, v54, v27
	s_waitcnt lgkmcnt(0)
	v_add_f32_e32 v27, v27, v29
	ds_bpermute_b32 v29, v55, v27
	s_waitcnt lgkmcnt(0)
	v_add_f32_e32 v27, v27, v29
	s_and_saveexec_b64 s[14:15], s[42:43]
	ds_write_b32 v176, v27 offset:2816
	s_or_b64 exec, exec, s[14:15]
	s_waitcnt lgkmcnt(0)
	s_barrier
	s_mov_b64 s[14:15], exec
	v_readlane_b32 s4, v246, 6
	v_readlane_b32 s5, v246, 7
	s_and_b64 s[4:5], s[14:15], s[4:5]
	s_mov_b64 exec, s[4:5]
	s_cbranch_execz .LBB0_804
	s_waitcnt lgkmcnt(0)
	ds_read_b128 v[0:3], v189
	s_ashr_i32 s57, s56, 31
	s_ashr_i32 s47, s46, 31
	s_lshl_b64 s[4:5], s[56:57], 16
	v_readlane_b32 s16, v246, 4
	v_readlane_b32 s17, v246, 5
	s_add_u32 s16, s16, s4
	s_addc_u32 s17, s17, s5
	s_lshl_b64 s[4:5], s[46:47], 2
	s_waitcnt lgkmcnt(0)
	v_mov_b32_e32 v4, v1
	v_mov_b32_e32 v5, v2
	v_mov_b32_e32 v1, v3
	s_add_u32 s4, s16, s4
	v_pk_add_f32 v[0:1], v[4:5], v[0:1]
	s_addc_u32 s5, s17, s5
	v_add_f32_e32 v2, v0, v1
	v_lshl_add_u64 v[0:1], v[178:179], 2, s[4:5]
	global_store_dword v[0:1], v2, off
